# P1 rstd table fill: 4 serialized load+vmcnt(0) round trips batched into one wait (dword loads into free v240-243)
# baseline (speedup 1.0000x reference)
;     __device__ __forceinline__ bool next(int i, Unit& u) const {
;         const long L = (long)(i >> psh) * G + c; if (L >= nwg) return false;
;         int wgid = (int)L; { const int q = nwg / NXCD, r = nwg % NXCD, xcd = wgid % NXCD, off = wgid / NXCD; wgid = (xcd < r ? xcd * (q + 1) : r * (q + 1) + (xcd - r) * q) + off; }
;         const int nig = WGM * nN, gid = wgid / nig, fm = gid * WGM, gsz = (nM - fm) < WGM ? (nM - fm) : WGM;
;         u.pm = fm + ((wgid % nig) % gsz); u.pn = (wgid % nig) / gsz; u.part = i & ((1 << psh) - 1); u.idx = i; return true;
.LBB0_319:
	s_or_b64 exec, exec, s[4:5]
	v_or_b32_sdwa v2, v3, v0 dst_sel:DWORD dst_unused:UNUSED_PAD src0_sel:DWORD src1_sel:BYTE_0
	s_add_u32 s18, s68, 0x10000
	v_ashrrev_i32_e32 v3, 31, v2
	s_addc_u32 s19, s69, 0
	v_lshlrev_b64 v[2:3], 6, v[2:3]
	v_lshl_add_u64 v[2:3], s[18:19], 0, v[2:3]
	global_load_dword v240, v[2:3], off
	v_or_b32_e32 v3, 2, v199
	v_mov_b64_e32 v[4:5], s[2:3]
	v_mad_i64_i32 v[4:5], s[0:1], v3, s71, v[4:5]
	s_mov_b64 s[0:1], 0x596
	s_nop 0
	v_cmp_gt_i64_e64 s[0:1], s[0:1], v[4:5]
	v_mov_b32_e32 v3, 0
	s_and_saveexec_b64 s[6:7], s[0:1]
	s_cbranch_execz .LBB0_325
	v_ashrrev_i32_e32 v3, 31, v4
	v_lshrrev_b32_e32 v3, 29, v3
	v_add_u32_e32 v6, v4, v3
	v_and_b32_e32 v3, -8, v6
	v_sub_u32_e32 v3, v4, v3
	v_cmp_lt_i32_e64 s[4:5], 5, v3
	s_and_saveexec_b64 s[8:9], s[4:5]
	s_xor_b64 s[4:5], exec, s[8:9]
	s_movk_i32 s8, 0xb2
	v_mad_u64_u32 v[4:5], s[8:9], v3, s8, 6
	s_or_saveexec_b64 s[4:5], s[4:5]
	v_ashrrev_i32_e32 v5, 3, v6
	s_xor_b64 exec, exec, s[4:5]
	s_movk_i32 s8, 0xb3
	v_mul_lo_u32 v4, v3, s8
	s_or_b64 exec, exec, s[4:5]
	v_add_u32_e32 v3, v4, v5
	s_mov_b32 s4, 0x2e8ba2e9
	v_mul_hi_i32 v4, v3, s4
	v_lshrrev_b32_e32 v5, 31, v4
	v_ashrrev_i32_e32 v4, 4, v4
	v_add_u32_e32 v4, v4, v5
	v_lshlrev_b32_e32 v5, 2, v4
	v_sub_u32_e32 v6, 0x41, v5
	v_min_i32_e32 v6, 4, v6
	v_sub_u32_e32 v7, 0, v6
	v_max_i32_e32 v6, v6, v7
	v_cvt_f32_u32_e32 v7, v6
	s_movk_i32 s4, 0x58
	v_mul_lo_u32 v4, v4, s4
	v_sub_u32_e32 v3, v3, v4
	v_rcp_iflag_f32_e32 v7, v7
	v_sub_u32_e32 v8, 0, v3
	v_ashrrev_i32_e32 v4, 31, v3
	v_max_i32_e32 v3, v3, v8
	v_mul_f32_e32 v7, 0x4f7ffffe, v7
	v_cvt_u32_f32_e32 v7, v7
	v_sub_u32_e32 v8, 0, v6
	v_mul_lo_u32 v8, v8, v7
	v_mul_hi_u32 v8, v7, v8
	v_add_u32_e32 v7, v7, v8
	v_mul_hi_u32 v7, v3, v7
	v_mul_lo_u32 v7, v7, v6
	v_sub_u32_e32 v3, v3, v7
	v_sub_u32_e32 v7, v3, v6
	v_cmp_ge_u32_e64 s[4:5], v3, v6
	s_nop 1
	v_cndmask_b32_e64 v3, v3, v7, s[4:5]
	v_sub_u32_e32 v7, v3, v6
	v_cmp_ge_u32_e64 s[4:5], v3, v6
	s_nop 1
	v_cndmask_b32_e64 v3, v3, v7, s[4:5]
	v_xor_b32_e32 v3, v3, v4
	v_sub_u32_e32 v3, v3, v4
	v_add_lshl_u32 v3, v5, v3, 8
.LBB0_325:
	s_or_b64 exec, exec, s[6:7]
	v_or_b32_sdwa v4, v3, v0 dst_sel:DWORD dst_unused:UNUSED_PAD src0_sel:DWORD src1_sel:BYTE_0
	v_ashrrev_i32_e32 v5, 31, v4
	v_lshlrev_b64 v[4:5], 6, v[4:5]
	v_lshl_add_u64 v[4:5], s[18:19], 0, v[4:5]
	global_load_dword v241, v[4:5], off
	v_or_b32_e32 v3, 4, v199
	v_mov_b64_e32 v[6:7], s[2:3]
	v_mad_i64_i32 v[6:7], s[4:5], v3, s71, v[6:7]
	s_mov_b64 s[4:5], 0x596
	s_nop 0
	v_cmp_gt_i64_e64 s[4:5], s[4:5], v[6:7]
	v_mov_b32_e32 v3, 0
	s_and_saveexec_b64 s[8:9], s[4:5]
	s_cbranch_execz .LBB0_331
	v_ashrrev_i32_e32 v3, 31, v6
	v_lshrrev_b32_e32 v3, 29, v3
	v_add_u32_e32 v5, v6, v3
	v_and_b32_e32 v3, -8, v5
	v_sub_u32_e32 v3, v6, v3
	v_cmp_lt_i32_e64 s[6:7], 5, v3
	s_and_saveexec_b64 s[20:21], s[6:7]
	s_xor_b64 s[6:7], exec, s[20:21]
	s_movk_i32 s20, 0xb2
	v_mad_u64_u32 v[6:7], s[20:21], v3, s20, 6
	s_or_saveexec_b64 s[6:7], s[6:7]
	v_ashrrev_i32_e32 v5, 3, v5
	s_xor_b64 exec, exec, s[6:7]
	s_movk_i32 s20, 0xb3
	v_mul_lo_u32 v6, v3, s20
	s_or_b64 exec, exec, s[6:7]
	v_add_u32_e32 v3, v6, v5
	s_mov_b32 s6, 0x2e8ba2e9
	v_mul_hi_i32 v5, v3, s6
	v_lshrrev_b32_e32 v6, 31, v5
	v_ashrrev_i32_e32 v5, 4, v5
	v_add_u32_e32 v5, v5, v6
	v_lshlrev_b32_e32 v6, 2, v5
	v_sub_u32_e32 v7, 0x41, v6
	v_min_i32_e32 v7, 4, v7
	v_sub_u32_e32 v8, 0, v7
	v_max_i32_e32 v7, v7, v8
	v_cvt_f32_u32_e32 v8, v7
	s_movk_i32 s6, 0x58
	v_mul_lo_u32 v5, v5, s6
	v_sub_u32_e32 v3, v3, v5
	v_rcp_iflag_f32_e32 v8, v8
	v_sub_u32_e32 v9, 0, v3
	v_ashrrev_i32_e32 v5, 31, v3
	v_max_i32_e32 v3, v3, v9
	v_mul_f32_e32 v8, 0x4f7ffffe, v8
	v_cvt_u32_f32_e32 v8, v8
	v_sub_u32_e32 v9, 0, v7
	v_mul_lo_u32 v9, v9, v8
	v_mul_hi_u32 v9, v8, v9
	v_add_u32_e32 v8, v8, v9
	v_mul_hi_u32 v8, v3, v8
	v_mul_lo_u32 v8, v8, v7
	v_sub_u32_e32 v3, v3, v8
	v_sub_u32_e32 v8, v3, v7
	v_cmp_ge_u32_e64 s[6:7], v3, v7
	s_nop 1
	v_cndmask_b32_e64 v3, v3, v8, s[6:7]
	v_sub_u32_e32 v8, v3, v7
	v_cmp_ge_u32_e64 s[6:7], v3, v7
	s_nop 1
	v_cndmask_b32_e64 v3, v3, v8, s[6:7]
	v_xor_b32_e32 v3, v3, v5
	v_sub_u32_e32 v3, v3, v5
	v_add_lshl_u32 v3, v6, v3, 8
.LBB0_331:
	s_or_b64 exec, exec, s[8:9]
	v_or_b32_sdwa v6, v3, v0 dst_sel:DWORD dst_unused:UNUSED_PAD src0_sel:DWORD src1_sel:BYTE_0
	v_ashrrev_i32_e32 v7, 31, v6
	v_lshlrev_b64 v[6:7], 6, v[6:7]
	v_lshl_add_u64 v[6:7], s[18:19], 0, v[6:7]
	global_load_dword v242, v[6:7], off
	v_or_b32_e32 v3, 6, v199
	v_mov_b64_e32 v[8:9], s[2:3]
	v_mad_i64_i32 v[8:9], s[6:7], v3, s71, v[8:9]
	s_mov_b64 s[6:7], 0x596
	s_nop 0
	v_cmp_gt_i64_e64 s[6:7], s[6:7], v[8:9]
	v_mov_b32_e32 v3, 0
	s_and_saveexec_b64 s[20:21], s[6:7]
	s_cbranch_execz .LBB0_337
	v_ashrrev_i32_e32 v3, 31, v8
	v_lshrrev_b32_e32 v3, 29, v3
	v_add_u32_e32 v5, v8, v3
	v_and_b32_e32 v3, -8, v5
	v_sub_u32_e32 v3, v8, v3
	v_cmp_lt_i32_e64 s[8:9], 5, v3
	s_and_saveexec_b64 s[24:25], s[8:9]
	s_xor_b64 s[8:9], exec, s[24:25]
	s_movk_i32 s24, 0xb2
	v_mad_u64_u32 v[8:9], s[24:25], v3, s24, 6
	s_or_saveexec_b64 s[8:9], s[8:9]
	v_ashrrev_i32_e32 v5, 3, v5
	s_xor_b64 exec, exec, s[8:9]
	s_movk_i32 s24, 0xb3
	v_mul_lo_u32 v8, v3, s24
	s_or_b64 exec, exec, s[8:9]
	v_add_u32_e32 v3, v8, v5
	s_mov_b32 s8, 0x2e8ba2e9
	v_mul_hi_i32 v5, v3, s8
	v_lshrrev_b32_e32 v7, 31, v5
	v_ashrrev_i32_e32 v5, 4, v5
	v_add_u32_e32 v5, v5, v7
	v_lshlrev_b32_e32 v7, 2, v5
	v_sub_u32_e32 v8, 0x41, v7
	v_min_i32_e32 v8, 4, v8
	v_sub_u32_e32 v9, 0, v8
	v_max_i32_e32 v8, v8, v9
	v_cvt_f32_u32_e32 v9, v8
	s_movk_i32 s8, 0x58
	v_mul_lo_u32 v5, v5, s8
	v_sub_u32_e32 v3, v3, v5
	v_rcp_iflag_f32_e32 v9, v9
	v_sub_u32_e32 v10, 0, v3
	v_ashrrev_i32_e32 v5, 31, v3
	v_max_i32_e32 v3, v3, v10
	v_mul_f32_e32 v9, 0x4f7ffffe, v9
	v_cvt_u32_f32_e32 v9, v9
	v_sub_u32_e32 v10, 0, v8
	v_mul_lo_u32 v10, v10, v9
	v_mul_hi_u32 v10, v9, v10
	v_add_u32_e32 v9, v9, v10
	v_mul_hi_u32 v9, v3, v9
	v_mul_lo_u32 v9, v9, v8
	v_sub_u32_e32 v3, v3, v9
	v_sub_u32_e32 v9, v3, v8
	v_cmp_ge_u32_e64 s[8:9], v3, v8
	s_nop 1
	v_cndmask_b32_e64 v3, v3, v9, s[8:9]
	v_sub_u32_e32 v9, v3, v8
	v_cmp_ge_u32_e64 s[8:9], v3, v8
	s_nop 1
	v_cndmask_b32_e64 v3, v3, v9, s[8:9]
	v_xor_b32_e32 v3, v3, v5
	v_sub_u32_e32 v3, v3, v5
	v_add_lshl_u32 v3, v7, v3, 8
.LBB0_337:
	s_or_b64 exec, exec, s[20:21]
	v_or_b32_sdwa v8, v3, v0 dst_sel:DWORD dst_unused:UNUSED_PAD src0_sel:DWORD src1_sel:BYTE_0
	v_ashrrev_i32_e32 v9, 31, v8
	v_lshlrev_b64 v[8:9], 6, v[8:9]
	v_lshl_add_u64 v[8:9], s[18:19], 0, v[8:9]
	global_load_dword v243, v[8:9], off
	v_and_b32_e32 v3, 0x100, v0
	v_mov_b32_e32 v5, 2
	s_add_i32 s8, 0, 0x20800
	v_lshlrev_b32_e32 v3, 2, v3
	v_lshlrev_b32_sdwa v5, v5, v0 dst_sel:DWORD dst_unused:UNUSED_PAD src0_sel:DWORD src1_sel:BYTE_0
	v_add3_u32 v3, s8, v3, v5
	s_waitcnt vmcnt(0)
	s_and_saveexec_b64 s[8:9], vcc
	s_cbranch_execnz .LBB0_349
	s_or_b64 exec, exec, s[8:9]
	s_and_saveexec_b64 s[8:9], s[0:1]
	s_cbranch_execnz .LBB0_350

.LBB0_341:
	s_waitcnt vmcnt(0)
	ds_write_b32 v3, v243 offset:6144

.LBB0_349:
	ds_write_b32 v3, v240
	s_or_b64 exec, exec, s[8:9]
	s_and_saveexec_b64 s[8:9], s[0:1]
	s_cbranch_execz .LBB0_339
.LBB0_350:
	ds_write_b32 v3, v241 offset:2048
	s_or_b64 exec, exec, s[8:9]
	s_and_saveexec_b64 s[0:1], s[4:5]
	s_cbranch_execz .LBB0_340
.LBB0_351:
	ds_write_b32 v3, v242 offset:4096
	s_or_b64 exec, exec, s[0:1]
	s_and_saveexec_b64 s[0:1], s[6:7]
	s_cbranch_execnz .LBB0_341
	s_branch .LBB0_342
